# neighbourhood attention: same unconditional bias loads in the second (odd) step body
# speedup vs baseline: 1.0192x; 1.0081x over previous
; __device__ __forceinline__ int crow(int r, int h) { return (r & 3) + 8 * (r >> 2) + 4 * h; }
;     ...
;             const bool biased = BIAS && t < nlat;
;             if (biased) {
;                 const int drow = (kr0 + t - qr + 7) * 32;
;                 int qcl = qc, csl = cs; asm volatile("" : "+v"(qcl), "+v"(csl));
; #pragma unroll
;                 for (int r = 0; r < 16; ++r) {
;                     const int k0 = crow(r, h2), k1 = k0 + 32;
;                     int d0 = k0 - qcl + 15, d1 = k1 - qcl + 15; d0 = d0 < 0 ? 0 : (d0 > 30 ? 30 : d0); d1 = d1 < 0 ? 0 : (d1 > 30 ? 30 : d1);
;                     const float b0 = rpbL[drow + d0], b1 = rpbL[drow + d1];
.LBB0_532:
	v_readlane_b32 s78, v255, 2
	s_andn2_b64 vcc, exec, s[2:3]
	s_mov_b64 s[48:49], 0
	v_readlane_b32 s79, v255, 3
	s_cbranch_vccnz .LBB0_566
	v_mov_b32_e32 v114, v192
	v_mov_b32_e32 v167, v193
	s_add_i32 s4, s70, s71

; __device__ __forceinline__ int crow(int r, int h) { return (r & 3) + 8 * (r >> 2) + 4 * h; }
;     ...
;                     const int k0 = crow(r, h2), k1 = k0 + 32;
;                     int d0 = k0 - qcl + 15, d1 = k1 - qcl + 15; d0 = d0 < 0 ? 0 : (d0 > 30 ? 30 : d0); d1 = d1 < 0 ? 0 : (d1 > 30 ? 30 : d1);
;                     const float b0 = rpbL[drow + d0], b1 = rpbL[drow + d1];
	v_sub_u32_e32 v168, v188, v114
	v_med3_i32 v168, v168, -15, 15
	v_lshl_add_u32 v168, v168, 2, s4
	ds_read_b32 v98, v168 offset:45116

; __device__ __forceinline__ int crow(int r, int h) { return (r & 3) + 8 * (r >> 2) + 4 * h; }
;     ...
;                     const int k0 = crow(r, h2), k1 = k0 + 32;
;                     int d0 = k0 - qcl + 15, d1 = k1 - qcl + 15; d0 = d0 < 0 ? 0 : (d0 > 30 ? 30 : d0); d1 = d1 < 0 ? 0 : (d1 > 30 ? 30 : d1);
;                     const float b0 = rpbL[drow + d0], b1 = rpbL[drow + d1];
	v_sub_u32_e32 v168, v212, v114
	v_med3_i32 v168, v168, -15, 15
	v_lshl_add_u32 v168, v168, 2, s4
	ds_read_b32 v99, v168 offset:45116

; __device__ __forceinline__ int crow(int r, int h) { return (r & 3) + 8 * (r >> 2) + 4 * h; }
;     ...
;                     const int k0 = crow(r, h2), k1 = k0 + 32;
;                     int d0 = k0 - qcl + 15, d1 = k1 - qcl + 15; d0 = d0 < 0 ? 0 : (d0 > 30 ? 30 : d0); d1 = d1 < 0 ? 0 : (d1 > 30 ? 30 : d1);
;                     const float b0 = rpbL[drow + d0], b1 = rpbL[drow + d1];
	v_sub_u32_e32 v168, v214, v114
	v_med3_i32 v168, v168, -15, 15
	v_lshl_add_u32 v168, v168, 2, s4
	ds_read_b32 v100, v168 offset:45116

; __device__ __forceinline__ int crow(int r, int h) { return (r & 3) + 8 * (r >> 2) + 4 * h; }
;     ...
;                     const int k0 = crow(r, h2), k1 = k0 + 32;
;                     int d0 = k0 - qcl + 15, d1 = k1 - qcl + 15; d0 = d0 < 0 ? 0 : (d0 > 30 ? 30 : d0); d1 = d1 < 0 ? 0 : (d1 > 30 ? 30 : d1);
;                     const float b0 = rpbL[drow + d0], b1 = rpbL[drow + d1];
	v_sub_u32_e32 v168, v216, v114
	v_med3_i32 v168, v168, -15, 15
	v_lshl_add_u32 v168, v168, 2, s4
	ds_read_b32 v101, v168 offset:45116

; __device__ __forceinline__ int crow(int r, int h) { return (r & 3) + 8 * (r >> 2) + 4 * h; }
;     ...
;                     const int k0 = crow(r, h2), k1 = k0 + 32;
;                     int d0 = k0 - qcl + 15, d1 = k1 - qcl + 15; d0 = d0 < 0 ? 0 : (d0 > 30 ? 30 : d0); d1 = d1 < 0 ? 0 : (d1 > 30 ? 30 : d1);
;                     const float b0 = rpbL[drow + d0], b1 = rpbL[drow + d1];
	v_sub_u32_e32 v168, v218, v114
	v_med3_i32 v168, v168, -15, 15
	v_lshl_add_u32 v168, v168, 2, s4
	ds_read_b32 v102, v168 offset:45116

; __device__ __forceinline__ int crow(int r, int h) { return (r & 3) + 8 * (r >> 2) + 4 * h; }
;     ...
;                     const int k0 = crow(r, h2), k1 = k0 + 32;
;                     int d0 = k0 - qcl + 15, d1 = k1 - qcl + 15; d0 = d0 < 0 ? 0 : (d0 > 30 ? 30 : d0); d1 = d1 < 0 ? 0 : (d1 > 30 ? 30 : d1);
;                     const float b0 = rpbL[drow + d0], b1 = rpbL[drow + d1];
	v_sub_u32_e32 v168, v220, v114
	v_med3_i32 v168, v168, -15, 15
	v_lshl_add_u32 v168, v168, 2, s4
	ds_read_b32 v103, v168 offset:45116

; __device__ __forceinline__ int crow(int r, int h) { return (r & 3) + 8 * (r >> 2) + 4 * h; }
;     ...
;                     const int k0 = crow(r, h2), k1 = k0 + 32;
;                     int d0 = k0 - qcl + 15, d1 = k1 - qcl + 15; d0 = d0 < 0 ? 0 : (d0 > 30 ? 30 : d0); d1 = d1 < 0 ? 0 : (d1 > 30 ? 30 : d1);
;                     const float b0 = rpbL[drow + d0], b1 = rpbL[drow + d1];
	v_sub_u32_e32 v168, v222, v114
	v_med3_i32 v168, v168, -15, 15
	v_lshl_add_u32 v168, v168, 2, s4
	ds_read_b32 v104, v168 offset:45116

; __device__ __forceinline__ int crow(int r, int h) { return (r & 3) + 8 * (r >> 2) + 4 * h; }
;     ...
;                     const int k0 = crow(r, h2), k1 = k0 + 32;
;                     int d0 = k0 - qcl + 15, d1 = k1 - qcl + 15; d0 = d0 < 0 ? 0 : (d0 > 30 ? 30 : d0); d1 = d1 < 0 ? 0 : (d1 > 30 ? 30 : d1);
;                     const float b0 = rpbL[drow + d0], b1 = rpbL[drow + d1];
	v_sub_u32_e32 v168, v224, v114
	v_med3_i32 v168, v168, -15, 15
	v_lshl_add_u32 v168, v168, 2, s4
	ds_read_b32 v105, v168 offset:45116

; __device__ __forceinline__ int crow(int r, int h) { return (r & 3) + 8 * (r >> 2) + 4 * h; }
;     ...
;                     const int k0 = crow(r, h2), k1 = k0 + 32;
;                     int d0 = k0 - qcl + 15, d1 = k1 - qcl + 15; d0 = d0 < 0 ? 0 : (d0 > 30 ? 30 : d0); d1 = d1 < 0 ? 0 : (d1 > 30 ? 30 : d1);
;                     const float b0 = rpbL[drow + d0], b1 = rpbL[drow + d1];
	v_sub_u32_e32 v168, v226, v114
	v_med3_i32 v168, v168, -15, 15
	v_lshl_add_u32 v168, v168, 2, s4
	ds_read_b32 v106, v168 offset:45116

; __device__ __forceinline__ int crow(int r, int h) { return (r & 3) + 8 * (r >> 2) + 4 * h; }
;     ...
;                     const int k0 = crow(r, h2), k1 = k0 + 32;
;                     int d0 = k0 - qcl + 15, d1 = k1 - qcl + 15; d0 = d0 < 0 ? 0 : (d0 > 30 ? 30 : d0); d1 = d1 < 0 ? 0 : (d1 > 30 ? 30 : d1);
;                     const float b0 = rpbL[drow + d0], b1 = rpbL[drow + d1];
	v_sub_u32_e32 v168, v228, v114
	v_med3_i32 v168, v168, -15, 15
	v_lshl_add_u32 v168, v168, 2, s4
	ds_read_b32 v107, v168 offset:45116

; __device__ __forceinline__ int crow(int r, int h) { return (r & 3) + 8 * (r >> 2) + 4 * h; }
;     ...
;                     const int k0 = crow(r, h2), k1 = k0 + 32;
;                     int d0 = k0 - qcl + 15, d1 = k1 - qcl + 15; d0 = d0 < 0 ? 0 : (d0 > 30 ? 30 : d0); d1 = d1 < 0 ? 0 : (d1 > 30 ? 30 : d1);
;                     const float b0 = rpbL[drow + d0], b1 = rpbL[drow + d1];
	v_sub_u32_e32 v168, v230, v114
	v_med3_i32 v168, v168, -15, 15
	v_lshl_add_u32 v168, v168, 2, s4
	ds_read_b32 v108, v168 offset:45116

; __device__ __forceinline__ int crow(int r, int h) { return (r & 3) + 8 * (r >> 2) + 4 * h; }
;     ...
;                     const int k0 = crow(r, h2), k1 = k0 + 32;
;                     int d0 = k0 - qcl + 15, d1 = k1 - qcl + 15; d0 = d0 < 0 ? 0 : (d0 > 30 ? 30 : d0); d1 = d1 < 0 ? 0 : (d1 > 30 ? 30 : d1);
;                     const float b0 = rpbL[drow + d0], b1 = rpbL[drow + d1];
	v_sub_u32_e32 v168, v232, v114
	v_med3_i32 v168, v168, -15, 15
	v_lshl_add_u32 v168, v168, 2, s4
	ds_read_b32 v109, v168 offset:45116

; __device__ __forceinline__ int crow(int r, int h) { return (r & 3) + 8 * (r >> 2) + 4 * h; }
;     ...
;                     const int k0 = crow(r, h2), k1 = k0 + 32;
;                     int d0 = k0 - qcl + 15, d1 = k1 - qcl + 15; d0 = d0 < 0 ? 0 : (d0 > 30 ? 30 : d0); d1 = d1 < 0 ? 0 : (d1 > 30 ? 30 : d1);
;                     const float b0 = rpbL[drow + d0], b1 = rpbL[drow + d1];
	v_sub_u32_e32 v168, v234, v114
	v_med3_i32 v168, v168, -15, 15
	v_lshl_add_u32 v168, v168, 2, s4
	ds_read_b32 v110, v168 offset:45116

; __device__ __forceinline__ int crow(int r, int h) { return (r & 3) + 8 * (r >> 2) + 4 * h; }
;     ...
;                     const int k0 = crow(r, h2), k1 = k0 + 32;
;                     int d0 = k0 - qcl + 15, d1 = k1 - qcl + 15; d0 = d0 < 0 ? 0 : (d0 > 30 ? 30 : d0); d1 = d1 < 0 ? 0 : (d1 > 30 ? 30 : d1);
;                     const float b0 = rpbL[drow + d0], b1 = rpbL[drow + d1];
	v_sub_u32_e32 v168, v236, v114
	v_med3_i32 v168, v168, -15, 15
	v_lshl_add_u32 v168, v168, 2, s4
	ds_read_b32 v111, v168 offset:45116

; __device__ __forceinline__ int crow(int r, int h) { return (r & 3) + 8 * (r >> 2) + 4 * h; }
;     ...
;                     const int k0 = crow(r, h2), k1 = k0 + 32;
;                     int d0 = k0 - qcl + 15, d1 = k1 - qcl + 15; d0 = d0 < 0 ? 0 : (d0 > 30 ? 30 : d0); d1 = d1 < 0 ? 0 : (d1 > 30 ? 30 : d1);
;                     const float b0 = rpbL[drow + d0], b1 = rpbL[drow + d1];
	v_sub_u32_e32 v168, v238, v114
	v_med3_i32 v168, v168, -15, 15
	v_lshl_add_u32 v168, v168, 2, s4
	ds_read_b32 v112, v168 offset:45116

; __device__ __forceinline__ int crow(int r, int h) { return (r & 3) + 8 * (r >> 2) + 4 * h; }
;     ...
;                     const int k0 = crow(r, h2), k1 = k0 + 32;
;                     int d0 = k0 - qcl + 15, d1 = k1 - qcl + 15; d0 = d0 < 0 ? 0 : (d0 > 30 ? 30 : d0); d1 = d1 < 0 ? 0 : (d1 > 30 ? 30 : d1);
;                     const float b0 = rpbL[drow + d0], b1 = rpbL[drow + d1];
	v_sub_u32_e32 v168, v240, v114
	v_med3_i32 v168, v168, -15, 15
	v_lshl_add_u32 v168, v168, 2, s4
	ds_read_b32 v113, v168 offset:45116

;     ...
;                     s0[r] = ((unsigned)(k0 - csl) < 16u) ? s0[r] * C2S + b0 * LOG2E : -1e30f;
	s_waitcnt lgkmcnt(0)
	v_sub_u32_e32 v169, v188, v167
	v_cmp_gt_u32_e32 vcc, 16, v169
	v_mul_f32_e32 v98, s21, v98
	v_mul_f32_e32 v168, s20, v82
	v_add_f32_e32 v98, v168, v98
	v_cndmask_b32_e32 v98, v202, v98, vcc

;     ...
;                     s0[r] = ((unsigned)(k0 - csl) < 16u) ? s0[r] * C2S + b0 * LOG2E : -1e30f;
	v_sub_u32_e32 v169, v212, v167
	v_cmp_gt_u32_e32 vcc, 16, v169
	v_mul_f32_e32 v99, s21, v99
	v_mul_f32_e32 v168, s20, v83
	v_add_f32_e32 v99, v168, v99
	v_cndmask_b32_e32 v99, v202, v99, vcc

;     ...
;                     s0[r] = ((unsigned)(k0 - csl) < 16u) ? s0[r] * C2S + b0 * LOG2E : -1e30f;
	v_sub_u32_e32 v169, v214, v167
	v_cmp_gt_u32_e32 vcc, 16, v169
	v_mul_f32_e32 v100, s21, v100
	v_mul_f32_e32 v168, s20, v84
	v_add_f32_e32 v100, v168, v100
	v_cndmask_b32_e32 v100, v202, v100, vcc

;     ...
;                     s0[r] = ((unsigned)(k0 - csl) < 16u) ? s0[r] * C2S + b0 * LOG2E : -1e30f;
	v_sub_u32_e32 v169, v216, v167
	v_cmp_gt_u32_e32 vcc, 16, v169
	v_mul_f32_e32 v101, s21, v101
	v_mul_f32_e32 v168, s20, v85
	v_add_f32_e32 v101, v168, v101
	v_cndmask_b32_e32 v101, v202, v101, vcc

;     ...
;                     s0[r] = ((unsigned)(k0 - csl) < 16u) ? s0[r] * C2S + b0 * LOG2E : -1e30f;
	v_sub_u32_e32 v169, v218, v167
	v_cmp_gt_u32_e32 vcc, 16, v169
	v_mul_f32_e32 v102, s21, v102
	v_mul_f32_e32 v168, s20, v86
	v_add_f32_e32 v102, v168, v102
	v_cndmask_b32_e32 v102, v202, v102, vcc

;     ...
;                     s0[r] = ((unsigned)(k0 - csl) < 16u) ? s0[r] * C2S + b0 * LOG2E : -1e30f;
	v_sub_u32_e32 v169, v220, v167
	v_cmp_gt_u32_e32 vcc, 16, v169
	v_mul_f32_e32 v103, s21, v103
	v_mul_f32_e32 v168, s20, v87
	v_add_f32_e32 v103, v168, v103
	v_cndmask_b32_e32 v103, v202, v103, vcc

;     ...
;                     s0[r] = ((unsigned)(k0 - csl) < 16u) ? s0[r] * C2S + b0 * LOG2E : -1e30f;
	v_sub_u32_e32 v169, v222, v167
	v_cmp_gt_u32_e32 vcc, 16, v169
	v_mul_f32_e32 v104, s21, v104
	v_mul_f32_e32 v168, s20, v88
	v_add_f32_e32 v104, v168, v104
	v_cndmask_b32_e32 v104, v202, v104, vcc

;     ...
;                     s0[r] = ((unsigned)(k0 - csl) < 16u) ? s0[r] * C2S + b0 * LOG2E : -1e30f;
	v_sub_u32_e32 v169, v224, v167
	v_cmp_gt_u32_e32 vcc, 16, v169
	v_mul_f32_e32 v105, s21, v105
	v_mul_f32_e32 v168, s20, v89
	v_add_f32_e32 v105, v168, v105
	v_cndmask_b32_e32 v105, v202, v105, vcc

;     ...
;                     s0[r] = ((unsigned)(k0 - csl) < 16u) ? s0[r] * C2S + b0 * LOG2E : -1e30f;
	v_sub_u32_e32 v169, v226, v167
	v_cmp_gt_u32_e32 vcc, 16, v169
	v_mul_f32_e32 v106, s21, v106
	v_mul_f32_e32 v168, s20, v90
	v_add_f32_e32 v106, v168, v106
	v_cndmask_b32_e32 v106, v202, v106, vcc

;     ...
;                     s0[r] = ((unsigned)(k0 - csl) < 16u) ? s0[r] * C2S + b0 * LOG2E : -1e30f;
	v_sub_u32_e32 v169, v228, v167
	v_cmp_gt_u32_e32 vcc, 16, v169
	v_mul_f32_e32 v107, s21, v107
	v_mul_f32_e32 v168, s20, v91
	v_add_f32_e32 v107, v168, v107
	v_cndmask_b32_e32 v107, v202, v107, vcc

;     ...
;                     s0[r] = ((unsigned)(k0 - csl) < 16u) ? s0[r] * C2S + b0 * LOG2E : -1e30f;
	v_sub_u32_e32 v169, v230, v167
	v_cmp_gt_u32_e32 vcc, 16, v169
	v_mul_f32_e32 v108, s21, v108
	v_mul_f32_e32 v168, s20, v92
	v_add_f32_e32 v108, v168, v108
	v_cndmask_b32_e32 v108, v202, v108, vcc

;     ...
;                     s0[r] = ((unsigned)(k0 - csl) < 16u) ? s0[r] * C2S + b0 * LOG2E : -1e30f;
	v_sub_u32_e32 v169, v232, v167
	v_cmp_gt_u32_e32 vcc, 16, v169
	v_mul_f32_e32 v109, s21, v109
	v_mul_f32_e32 v168, s20, v93
	v_add_f32_e32 v109, v168, v109
	v_cndmask_b32_e32 v109, v202, v109, vcc

;     ...
;                     s0[r] = ((unsigned)(k0 - csl) < 16u) ? s0[r] * C2S + b0 * LOG2E : -1e30f;
	v_sub_u32_e32 v169, v234, v167
	v_cmp_gt_u32_e32 vcc, 16, v169
	v_mul_f32_e32 v110, s21, v110
	v_mul_f32_e32 v168, s20, v94
	v_add_f32_e32 v110, v168, v110
	v_cndmask_b32_e32 v110, v202, v110, vcc

;     ...
;                     s0[r] = ((unsigned)(k0 - csl) < 16u) ? s0[r] * C2S + b0 * LOG2E : -1e30f;
	v_sub_u32_e32 v169, v236, v167
	v_cmp_gt_u32_e32 vcc, 16, v169
	v_mul_f32_e32 v111, s21, v111
	v_mul_f32_e32 v168, s20, v95
	v_add_f32_e32 v111, v168, v111
	v_cndmask_b32_e32 v111, v202, v111, vcc

;     ...
;                     s0[r] = ((unsigned)(k0 - csl) < 16u) ? s0[r] * C2S + b0 * LOG2E : -1e30f;
	v_sub_u32_e32 v169, v238, v167
	v_cmp_gt_u32_e32 vcc, 16, v169
	v_mul_f32_e32 v112, s21, v112
	v_mul_f32_e32 v168, s20, v96
	v_add_f32_e32 v112, v168, v112
	v_cndmask_b32_e32 v112, v202, v112, vcc

;     ...
;                     s0[r] = ((unsigned)(k0 - csl) < 16u) ? s0[r] * C2S + b0 * LOG2E : -1e30f;
	v_sub_u32_e32 v169, v240, v167
	v_cmp_gt_u32_e32 vcc, 16, v169
	v_mul_f32_e32 v113, s21, v113
	v_mul_f32_e32 v168, s20, v97
	v_add_f32_e32 v113, v168, v113
	v_cndmask_b32_e32 v113, v202, v113, vcc

; __device__ __forceinline__ int crow(int r, int h) { return (r & 3) + 8 * (r >> 2) + 4 * h; }
;     ...
;                     const int k0 = crow(r, h2), k1 = k0 + 32;
;                     int d0 = k0 - qcl + 15, d1 = k1 - qcl + 15; d0 = d0 < 0 ? 0 : (d0 > 30 ? 30 : d0); d1 = d1 < 0 ? 0 : (d1 > 30 ? 30 : d1);
;                     const float b0 = rpbL[drow + d0], b1 = rpbL[drow + d1];
	v_sub_u32_e32 v168, v211, v114
	v_med3_i32 v168, v168, -15, 15
	v_lshl_add_u32 v168, v168, 2, s4
	ds_read_b32 v115, v168 offset:45116

; __device__ __forceinline__ int crow(int r, int h) { return (r & 3) + 8 * (r >> 2) + 4 * h; }
;     ...
;                     const int k0 = crow(r, h2), k1 = k0 + 32;
;                     int d0 = k0 - qcl + 15, d1 = k1 - qcl + 15; d0 = d0 < 0 ? 0 : (d0 > 30 ? 30 : d0); d1 = d1 < 0 ? 0 : (d1 > 30 ? 30 : d1);
;                     const float b0 = rpbL[drow + d0], b1 = rpbL[drow + d1];
	v_sub_u32_e32 v168, v213, v114
	v_med3_i32 v168, v168, -15, 15
	v_lshl_add_u32 v168, v168, 2, s4
	ds_read_b32 v117, v168 offset:45116

; __device__ __forceinline__ int crow(int r, int h) { return (r & 3) + 8 * (r >> 2) + 4 * h; }
;     ...
;                     const int k0 = crow(r, h2), k1 = k0 + 32;
;                     int d0 = k0 - qcl + 15, d1 = k1 - qcl + 15; d0 = d0 < 0 ? 0 : (d0 > 30 ? 30 : d0); d1 = d1 < 0 ? 0 : (d1 > 30 ? 30 : d1);
;                     const float b0 = rpbL[drow + d0], b1 = rpbL[drow + d1];
	v_sub_u32_e32 v168, v215, v114
	v_med3_i32 v168, v168, -15, 15
	v_lshl_add_u32 v168, v168, 2, s4
	ds_read_b32 v83, v168 offset:45116

; __device__ __forceinline__ int crow(int r, int h) { return (r & 3) + 8 * (r >> 2) + 4 * h; }
;     ...
;                     const int k0 = crow(r, h2), k1 = k0 + 32;
;                     int d0 = k0 - qcl + 15, d1 = k1 - qcl + 15; d0 = d0 < 0 ? 0 : (d0 > 30 ? 30 : d0); d1 = d1 < 0 ? 0 : (d1 > 30 ? 30 : d1);
;                     const float b0 = rpbL[drow + d0], b1 = rpbL[drow + d1];
	v_sub_u32_e32 v168, v217, v114
	v_med3_i32 v168, v168, -15, 15
	v_lshl_add_u32 v168, v168, 2, s4
	ds_read_b32 v119, v168 offset:45116

; __device__ __forceinline__ int crow(int r, int h) { return (r & 3) + 8 * (r >> 2) + 4 * h; }
;     ...
;                     const int k0 = crow(r, h2), k1 = k0 + 32;
;                     int d0 = k0 - qcl + 15, d1 = k1 - qcl + 15; d0 = d0 < 0 ? 0 : (d0 > 30 ? 30 : d0); d1 = d1 < 0 ? 0 : (d1 > 30 ? 30 : d1);
;                     const float b0 = rpbL[drow + d0], b1 = rpbL[drow + d1];
	v_sub_u32_e32 v168, v219, v114
	v_med3_i32 v168, v168, -15, 15
	v_lshl_add_u32 v168, v168, 2, s4
	ds_read_b32 v85, v168 offset:45116

; __device__ __forceinline__ int crow(int r, int h) { return (r & 3) + 8 * (r >> 2) + 4 * h; }
;     ...
;                     const int k0 = crow(r, h2), k1 = k0 + 32;
;                     int d0 = k0 - qcl + 15, d1 = k1 - qcl + 15; d0 = d0 < 0 ? 0 : (d0 > 30 ? 30 : d0); d1 = d1 < 0 ? 0 : (d1 > 30 ? 30 : d1);
;                     const float b0 = rpbL[drow + d0], b1 = rpbL[drow + d1];
	v_sub_u32_e32 v168, v221, v114
	v_med3_i32 v168, v168, -15, 15
	v_lshl_add_u32 v168, v168, 2, s4
	ds_read_b32 v121, v168 offset:45116

; __device__ __forceinline__ int crow(int r, int h) { return (r & 3) + 8 * (r >> 2) + 4 * h; }
;     ...
;                     const int k0 = crow(r, h2), k1 = k0 + 32;
;                     int d0 = k0 - qcl + 15, d1 = k1 - qcl + 15; d0 = d0 < 0 ? 0 : (d0 > 30 ? 30 : d0); d1 = d1 < 0 ? 0 : (d1 > 30 ? 30 : d1);
;                     const float b0 = rpbL[drow + d0], b1 = rpbL[drow + d1];
	v_sub_u32_e32 v168, v223, v114
	v_med3_i32 v168, v168, -15, 15
	v_lshl_add_u32 v168, v168, 2, s4
	ds_read_b32 v87, v168 offset:45116

; __device__ __forceinline__ int crow(int r, int h) { return (r & 3) + 8 * (r >> 2) + 4 * h; }
;     ...
;                     const int k0 = crow(r, h2), k1 = k0 + 32;
;                     int d0 = k0 - qcl + 15, d1 = k1 - qcl + 15; d0 = d0 < 0 ? 0 : (d0 > 30 ? 30 : d0); d1 = d1 < 0 ? 0 : (d1 > 30 ? 30 : d1);
;                     const float b0 = rpbL[drow + d0], b1 = rpbL[drow + d1];
	v_sub_u32_e32 v168, v225, v114
	v_med3_i32 v168, v168, -15, 15
	v_lshl_add_u32 v168, v168, 2, s4
	ds_read_b32 v123, v168 offset:45116

; __device__ __forceinline__ int crow(int r, int h) { return (r & 3) + 8 * (r >> 2) + 4 * h; }
;     ...
;                     const int k0 = crow(r, h2), k1 = k0 + 32;
;                     int d0 = k0 - qcl + 15, d1 = k1 - qcl + 15; d0 = d0 < 0 ? 0 : (d0 > 30 ? 30 : d0); d1 = d1 < 0 ? 0 : (d1 > 30 ? 30 : d1);
;                     const float b0 = rpbL[drow + d0], b1 = rpbL[drow + d1];
	v_sub_u32_e32 v168, v227, v114
	v_med3_i32 v168, v168, -15, 15
	v_lshl_add_u32 v168, v168, 2, s4
	ds_read_b32 v89, v168 offset:45116

; __device__ __forceinline__ int crow(int r, int h) { return (r & 3) + 8 * (r >> 2) + 4 * h; }
;     ...
;                     const int k0 = crow(r, h2), k1 = k0 + 32;
;                     int d0 = k0 - qcl + 15, d1 = k1 - qcl + 15; d0 = d0 < 0 ? 0 : (d0 > 30 ? 30 : d0); d1 = d1 < 0 ? 0 : (d1 > 30 ? 30 : d1);
;                     const float b0 = rpbL[drow + d0], b1 = rpbL[drow + d1];
	v_sub_u32_e32 v168, v229, v114
	v_med3_i32 v168, v168, -15, 15
	v_lshl_add_u32 v168, v168, 2, s4
	ds_read_b32 v125, v168 offset:45116

; __device__ __forceinline__ int crow(int r, int h) { return (r & 3) + 8 * (r >> 2) + 4 * h; }
;     ...
;                     const int k0 = crow(r, h2), k1 = k0 + 32;
;                     int d0 = k0 - qcl + 15, d1 = k1 - qcl + 15; d0 = d0 < 0 ? 0 : (d0 > 30 ? 30 : d0); d1 = d1 < 0 ? 0 : (d1 > 30 ? 30 : d1);
;                     const float b0 = rpbL[drow + d0], b1 = rpbL[drow + d1];
	v_sub_u32_e32 v168, v231, v114
	v_med3_i32 v168, v168, -15, 15
	v_lshl_add_u32 v168, v168, 2, s4
	ds_read_b32 v91, v168 offset:45116

; __device__ __forceinline__ int crow(int r, int h) { return (r & 3) + 8 * (r >> 2) + 4 * h; }
;     ...
;                     const int k0 = crow(r, h2), k1 = k0 + 32;
;                     int d0 = k0 - qcl + 15, d1 = k1 - qcl + 15; d0 = d0 < 0 ? 0 : (d0 > 30 ? 30 : d0); d1 = d1 < 0 ? 0 : (d1 > 30 ? 30 : d1);
;                     const float b0 = rpbL[drow + d0], b1 = rpbL[drow + d1];
	v_sub_u32_e32 v168, v233, v114
	v_med3_i32 v168, v168, -15, 15
	v_lshl_add_u32 v168, v168, 2, s4
	ds_read_b32 v127, v168 offset:45116

; __device__ __forceinline__ int crow(int r, int h) { return (r & 3) + 8 * (r >> 2) + 4 * h; }
;     ...
;                     const int k0 = crow(r, h2), k1 = k0 + 32;
;                     int d0 = k0 - qcl + 15, d1 = k1 - qcl + 15; d0 = d0 < 0 ? 0 : (d0 > 30 ? 30 : d0); d1 = d1 < 0 ? 0 : (d1 > 30 ? 30 : d1);
;                     const float b0 = rpbL[drow + d0], b1 = rpbL[drow + d1];
	v_sub_u32_e32 v168, v235, v114
	v_med3_i32 v168, v168, -15, 15
	v_lshl_add_u32 v168, v168, 2, s4
	ds_read_b32 v93, v168 offset:45116

; __device__ __forceinline__ int crow(int r, int h) { return (r & 3) + 8 * (r >> 2) + 4 * h; }
;     ...
;                     const int k0 = crow(r, h2), k1 = k0 + 32;
;                     int d0 = k0 - qcl + 15, d1 = k1 - qcl + 15; d0 = d0 < 0 ? 0 : (d0 > 30 ? 30 : d0); d1 = d1 < 0 ? 0 : (d1 > 30 ? 30 : d1);
;                     const float b0 = rpbL[drow + d0], b1 = rpbL[drow + d1];
	v_sub_u32_e32 v168, v237, v114
	v_med3_i32 v168, v168, -15, 15
	v_lshl_add_u32 v168, v168, 2, s4
	ds_read_b32 v129, v168 offset:45116

; __device__ __forceinline__ int crow(int r, int h) { return (r & 3) + 8 * (r >> 2) + 4 * h; }
;     ...
;                     const int k0 = crow(r, h2), k1 = k0 + 32;
;                     int d0 = k0 - qcl + 15, d1 = k1 - qcl + 15; d0 = d0 < 0 ? 0 : (d0 > 30 ? 30 : d0); d1 = d1 < 0 ? 0 : (d1 > 30 ? 30 : d1);
;                     const float b0 = rpbL[drow + d0], b1 = rpbL[drow + d1];
	v_sub_u32_e32 v168, v239, v114
	v_med3_i32 v168, v168, -15, 15
	v_lshl_add_u32 v168, v168, 2, s4
	ds_read_b32 v165, v168 offset:45116

; __device__ __forceinline__ int crow(int r, int h) { return (r & 3) + 8 * (r >> 2) + 4 * h; }
;     ...
;                     const int k0 = crow(r, h2), k1 = k0 + 32;
;                     int d0 = k0 - qcl + 15, d1 = k1 - qcl + 15; d0 = d0 < 0 ? 0 : (d0 > 30 ? 30 : d0); d1 = d1 < 0 ? 0 : (d1 > 30 ? 30 : d1);
;                     const float b0 = rpbL[drow + d0], b1 = rpbL[drow + d1];
	v_sub_u32_e32 v168, v241, v114
	v_med3_i32 v168, v168, -15, 15
	v_lshl_add_u32 v168, v168, 2, s4
	ds_read_b32 v95, v168 offset:45116

; __device__ __forceinline__ int crow(int r, int h) { return (r & 3) + 8 * (r >> 2) + 4 * h; }
;     ...
;                 for (int r = 0; r < 16; ++r) {
;                     const int k0 = crow(r, h2), k1 = k0 + 32;
;                     int d0 = k0 - qcl + 15, d1 = k1 - qcl + 15; d0 = d0 < 0 ? 0 : (d0 > 30 ? 30 : d0); d1 = d1 < 0 ? 0 : (d1 > 30 ? 30 : d1);
;                     const float b0 = rpbL[drow + d0], b1 = rpbL[drow + d1];
;                     s0[r] = ((unsigned)(k0 - csl) < 16u) ? s0[r] * C2S + b0 * LOG2E : -1e30f;
;                     s1[r] = ((unsigned)(k1 - csl) < 16u) ? s1[r] * C2S + b1 * LOG2E : -1e30f;
;                 }
	v_mov_b32_e32 v114, v66
	v_sub_u32_e32 v82, v211, v167
	s_waitcnt lgkmcnt(14)
	v_pk_mul_f32 v[96:97], v[114:115], s[20:21]
	v_mov_b32_e32 v116, v67
	v_cmp_gt_u32_e32 vcc, 16, v82
	v_add_f32_e32 v66, v96, v97
	v_sub_u32_e32 v82, v213, v167
	v_pk_mul_f32 v[96:97], v[116:117], s[20:21]
	v_cndmask_b32_e32 v66, v202, v66, vcc
	v_cmp_gt_u32_e32 vcc, 16, v82
	v_add_f32_e32 v67, v96, v97
	v_sub_u32_e32 v82, v215, v167
	v_cndmask_b32_e32 v67, v202, v67, vcc
	v_cmp_gt_u32_e32 vcc, 16, v82
	v_mov_b32_e32 v82, v68
	s_waitcnt lgkmcnt(13)
	v_pk_mul_f32 v[82:83], v[82:83], s[20:21]
	v_mov_b32_e32 v118, v69
	v_add_f32_e32 v68, v82, v83
	v_sub_u32_e32 v82, v217, v167
	v_cndmask_b32_e32 v68, v202, v68, vcc
	v_cmp_gt_u32_e32 vcc, 16, v82
	s_waitcnt lgkmcnt(12)
	v_pk_mul_f32 v[82:83], v[118:119], s[20:21]
	v_mov_b32_e32 v84, v70
	v_add_f32_e32 v69, v82, v83
	v_sub_u32_e32 v82, v219, v167
	v_cndmask_b32_e32 v69, v202, v69, vcc
	v_cmp_gt_u32_e32 vcc, 16, v82
	s_waitcnt lgkmcnt(11)
	v_pk_mul_f32 v[82:83], v[84:85], s[20:21]
	v_mov_b32_e32 v120, v71
	v_add_f32_e32 v70, v82, v83
	v_sub_u32_e32 v82, v221, v167
	v_cndmask_b32_e32 v70, v202, v70, vcc
	v_cmp_gt_u32_e32 vcc, 16, v82
	s_waitcnt lgkmcnt(10)
	v_pk_mul_f32 v[82:83], v[120:121], s[20:21]
	v_mov_b32_e32 v86, v72
	v_add_f32_e32 v71, v82, v83
	v_sub_u32_e32 v82, v223, v167
	v_cndmask_b32_e32 v71, v202, v71, vcc
	v_cmp_gt_u32_e32 vcc, 16, v82
	s_waitcnt lgkmcnt(9)
	v_pk_mul_f32 v[82:83], v[86:87], s[20:21]
	v_mov_b32_e32 v122, v73
	v_add_f32_e32 v72, v82, v83
	v_sub_u32_e32 v82, v225, v167
	v_cndmask_b32_e32 v72, v202, v72, vcc
	v_cmp_gt_u32_e32 vcc, 16, v82
	s_waitcnt lgkmcnt(8)
	v_pk_mul_f32 v[82:83], v[122:123], s[20:21]
	v_mov_b32_e32 v88, v74
	v_add_f32_e32 v73, v82, v83
	v_sub_u32_e32 v82, v227, v167
	v_cndmask_b32_e32 v73, v202, v73, vcc
	v_cmp_gt_u32_e32 vcc, 16, v82
	s_waitcnt lgkmcnt(7)
	v_pk_mul_f32 v[82:83], v[88:89], s[20:21]
	v_mov_b32_e32 v124, v75
	v_add_f32_e32 v74, v82, v83
	v_sub_u32_e32 v82, v229, v167
	v_cndmask_b32_e32 v74, v202, v74, vcc
	v_cmp_gt_u32_e32 vcc, 16, v82
	s_waitcnt lgkmcnt(6)
	v_pk_mul_f32 v[82:83], v[124:125], s[20:21]
	v_mov_b32_e32 v90, v76
	v_add_f32_e32 v75, v82, v83
	v_sub_u32_e32 v82, v231, v167
	v_cndmask_b32_e32 v75, v202, v75, vcc
	v_cmp_gt_u32_e32 vcc, 16, v82
	s_waitcnt lgkmcnt(5)
	v_pk_mul_f32 v[82:83], v[90:91], s[20:21]
	v_mov_b32_e32 v126, v77
	v_add_f32_e32 v76, v82, v83
	v_sub_u32_e32 v82, v233, v167
	v_cndmask_b32_e32 v76, v202, v76, vcc
	v_cmp_gt_u32_e32 vcc, 16, v82
	s_waitcnt lgkmcnt(4)
	v_pk_mul_f32 v[82:83], v[126:127], s[20:21]
	v_mov_b32_e32 v92, v78
	v_add_f32_e32 v77, v82, v83
	v_sub_u32_e32 v82, v235, v167
	v_cndmask_b32_e32 v77, v202, v77, vcc
	v_cmp_gt_u32_e32 vcc, 16, v82
	s_waitcnt lgkmcnt(3)
	v_pk_mul_f32 v[82:83], v[92:93], s[20:21]
	v_mov_b32_e32 v128, v79
	v_add_f32_e32 v78, v82, v83
	v_sub_u32_e32 v82, v237, v167
	v_cndmask_b32_e32 v78, v202, v78, vcc
	v_cmp_gt_u32_e32 vcc, 16, v82
	s_waitcnt lgkmcnt(2)
	v_pk_mul_f32 v[82:83], v[128:129], s[20:21]
	v_mov_b32_e32 v164, v80
	v_add_f32_e32 v79, v82, v83
	v_sub_u32_e32 v82, v239, v167
	v_cndmask_b32_e32 v79, v202, v79, vcc
	v_cmp_gt_u32_e32 vcc, 16, v82
	s_waitcnt lgkmcnt(1)
	v_pk_mul_f32 v[82:83], v[164:165], s[20:21]
	v_mov_b32_e32 v94, v81
	v_add_f32_e32 v80, v82, v83
	v_sub_u32_e32 v82, v241, v167
	v_cndmask_b32_e32 v80, v202, v80, vcc
	v_cmp_gt_u32_e32 vcc, 16, v82
	s_waitcnt lgkmcnt(0)
	v_pk_mul_f32 v[82:83], v[94:95], s[20:21]
	s_mov_b64 s[48:49], -1
	v_add_f32_e32 v81, v82, v83
	v_mov_b64_e32 v[82:83], v[98:99]
	v_cndmask_b32_e32 v81, v202, v81, vcc
	v_mov_b64_e32 v[84:85], v[100:101]
	v_mov_b64_e32 v[86:87], v[102:103]
	v_mov_b64_e32 v[88:89], v[104:105]
	v_mov_b64_e32 v[90:91], v[106:107]
	v_mov_b64_e32 v[92:93], v[108:109]
	v_mov_b64_e32 v[94:95], v[110:111]
	v_mov_b64_e32 v[96:97], v[112:113]
